# c6 + knorm units: loads of 4 keys batched per trip (knorm now on phase-2 critical path)
# speedup vs baseline: 1.1640x; 1.0092x over previous
.LBB0_367:
.LBB0_368:
	s_add_u32 s15, s13, s6
	s_addc_u32 s16, s14, s7
	v_mov_b32_e32 v232, 0
	v_mov_b32_e32 v240, 0
	v_mov_b32_e32 v46, 0
	v_mov_b32_e32 v248, 0
	s_mov_b32 s17, s15
	s_mov_b32 s18, s16
	s_cmp_ge_i32 s17, s11
	s_cbranch_scc1 .Lkn_issued
	s_cmpk_gt_i32 s17, 0x7ff
	s_cselect_b64 s[54:55], -1, 0
	s_and_b64 s[54:55], s[8:9], s[54:55]
	s_add_u32 s19, s12, s6
	s_addc_u32 s27, 0, s7
	s_mov_b32 s33, s19
	s_mov_b32 s19, s27
	s_and_b64 s[54:55], s[54:55], exec
	s_cselect_b32 s19, s19, s18
	s_cselect_b32 s18, s33, s17
	s_cselect_b32 s17, s5, s3
	s_cselect_b32 s27, s4, s2
	s_lshl_b64 s[18:19], s[18:19], 11
	s_add_u32 s18, s27, s18
	s_addc_u32 s19, s17, s19
	v_lshl_add_u64 v[252:253], v[2:3], 2, s[18:19]
	global_load_dwordx4 v[232:235], v[252:253], off
	global_load_dwordx4 v[236:239], v[252:253], off offset:16
	s_add_u32 s17, s15, 1
	s_addc_u32 s18, s16, 0
	s_cmp_ge_i32 s17, s11
	s_cbranch_scc1 .Lkn_issued
	s_cmpk_gt_i32 s17, 0x7ff
	s_cselect_b64 s[54:55], -1, 0
	s_and_b64 s[54:55], s[8:9], s[54:55]
	s_add_u32 s19, s12, s6
	s_addc_u32 s27, 0, s7
	s_add_u32 s33, s19, 1
	s_addc_u32 s19, s27, 0
	s_and_b64 s[54:55], s[54:55], exec
	s_cselect_b32 s19, s19, s18
	s_cselect_b32 s18, s33, s17
	s_cselect_b32 s17, s5, s3
	s_cselect_b32 s27, s4, s2
	s_lshl_b64 s[18:19], s[18:19], 11
	s_add_u32 s18, s27, s18
	s_addc_u32 s19, s17, s19
	v_lshl_add_u64 v[252:253], v[2:3], 2, s[18:19]
	global_load_dwordx4 v[240:243], v[252:253], off
	global_load_dwordx4 v[244:247], v[252:253], off offset:16
	s_add_u32 s17, s15, 2
	s_addc_u32 s18, s16, 0
	s_cmp_ge_i32 s17, s11
	s_cbranch_scc1 .Lkn_issued
	s_cmpk_gt_i32 s17, 0x7ff
	s_cselect_b64 s[54:55], -1, 0
	s_and_b64 s[54:55], s[8:9], s[54:55]
	s_add_u32 s19, s12, s6
	s_addc_u32 s27, 0, s7
	s_add_u32 s33, s19, 2
	s_addc_u32 s19, s27, 0
	s_and_b64 s[54:55], s[54:55], exec
	s_cselect_b32 s19, s19, s18
	s_cselect_b32 s18, s33, s17
	s_cselect_b32 s17, s5, s3
	s_cselect_b32 s27, s4, s2
	s_lshl_b64 s[18:19], s[18:19], 11
	s_add_u32 s18, s27, s18
	s_addc_u32 s19, s17, s19
	v_lshl_add_u64 v[252:253], v[2:3], 2, s[18:19]
	global_load_dwordx4 v[46:49], v[252:253], off
	global_load_dwordx4 v[50:53], v[252:253], off offset:16
	s_add_u32 s17, s15, 3
	s_addc_u32 s18, s16, 0
	s_cmp_ge_i32 s17, s11
	s_cbranch_scc1 .Lkn_issued
	s_cmpk_gt_i32 s17, 0x7ff
	s_cselect_b64 s[54:55], -1, 0
	s_and_b64 s[54:55], s[8:9], s[54:55]
	s_add_u32 s19, s12, s6
	s_addc_u32 s27, 0, s7
	s_add_u32 s33, s19, 3
	s_addc_u32 s19, s27, 0
	s_and_b64 s[54:55], s[54:55], exec
	s_cselect_b32 s19, s19, s18
	s_cselect_b32 s18, s33, s17
	s_cselect_b32 s17, s5, s3
	s_cselect_b32 s27, s4, s2
	s_lshl_b64 s[18:19], s[18:19], 11
	s_add_u32 s18, s27, s18
	s_addc_u32 s19, s17, s19
	v_lshl_add_u64 v[252:253], v[2:3], 2, s[18:19]
	global_load_dwordx4 v[248:251], v[252:253], off
	global_load_dwordx4 v[6:9], v[252:253], off offset:16
.Lkn_issued:
	s_waitcnt vmcnt(0)
	s_cmp_ge_i32 s15, s11
	s_cbranch_scc1 .Lkn_red
	v_pk_mul_f32 v[232:233], v[232:233], v[232:233]
	v_pk_mul_f32 v[234:235], v[234:235], v[234:235]
	v_add_f32_e32 v232, v232, v233
	v_add_f32_e32 v232, v232, v234
	v_pk_mul_f32 v[236:237], v[236:237], v[236:237]
	v_add_f32_e32 v232, v232, v235
	v_add_f32_e32 v232, v232, v236
	v_pk_mul_f32 v[238:239], v[238:239], v[238:239]
	v_add_f32_e32 v232, v232, v237
	v_add_f32_e32 v232, v232, v238
	v_add_f32_e32 v232, v232, v239
	s_add_u32 s17, s15, 1
	s_cmp_ge_i32 s17, s11
	s_cbranch_scc1 .Lkn_red
	v_pk_mul_f32 v[240:241], v[240:241], v[240:241]
	v_pk_mul_f32 v[242:243], v[242:243], v[242:243]
	v_add_f32_e32 v240, v240, v241
	v_add_f32_e32 v240, v240, v242
	v_pk_mul_f32 v[244:245], v[244:245], v[244:245]
	v_add_f32_e32 v240, v240, v243
	v_add_f32_e32 v240, v240, v244
	v_pk_mul_f32 v[246:247], v[246:247], v[246:247]
	v_add_f32_e32 v240, v240, v245
	v_add_f32_e32 v240, v240, v246
	v_add_f32_e32 v240, v240, v247
	s_add_u32 s17, s15, 2
	s_cmp_ge_i32 s17, s11
	s_cbranch_scc1 .Lkn_red
	v_pk_mul_f32 v[46:47], v[46:47], v[46:47]
	v_pk_mul_f32 v[48:49], v[48:49], v[48:49]
	v_add_f32_e32 v46, v46, v47
	v_add_f32_e32 v46, v46, v48
	v_pk_mul_f32 v[50:51], v[50:51], v[50:51]
	v_add_f32_e32 v46, v46, v49
	v_add_f32_e32 v46, v46, v50
	v_pk_mul_f32 v[52:53], v[52:53], v[52:53]
	v_add_f32_e32 v46, v46, v51
	v_add_f32_e32 v46, v46, v52
	v_add_f32_e32 v46, v46, v53
	s_add_u32 s17, s15, 3
	s_cmp_ge_i32 s17, s11
	s_cbranch_scc1 .Lkn_red
	v_pk_mul_f32 v[248:249], v[248:249], v[248:249]
	v_pk_mul_f32 v[250:251], v[250:251], v[250:251]
	v_add_f32_e32 v248, v248, v249
	v_add_f32_e32 v248, v248, v250
	v_pk_mul_f32 v[6:7], v[6:7], v[6:7]
	v_add_f32_e32 v248, v248, v251
	v_add_f32_e32 v248, v248, v6
	v_pk_mul_f32 v[8:9], v[8:9], v[8:9]
	v_add_f32_e32 v248, v248, v7
	v_add_f32_e32 v248, v248, v8
	v_add_f32_e32 v248, v248, v9
.Lkn_red:
	s_nop 1
	v_add_f32_dpp v232, v232, v232 quad_perm:[1,0,3,2] row_mask:0xf bank_mask:0xf bound_ctrl:1
	v_add_f32_dpp v240, v240, v240 quad_perm:[1,0,3,2] row_mask:0xf bank_mask:0xf bound_ctrl:1
	v_add_f32_dpp v46, v46, v46 quad_perm:[1,0,3,2] row_mask:0xf bank_mask:0xf bound_ctrl:1
	v_add_f32_dpp v248, v248, v248 quad_perm:[1,0,3,2] row_mask:0xf bank_mask:0xf bound_ctrl:1
	s_nop 0
	v_add_f32_dpp v232, v232, v232 quad_perm:[2,3,0,1] row_mask:0xf bank_mask:0xf bound_ctrl:1
	v_add_f32_dpp v240, v240, v240 quad_perm:[2,3,0,1] row_mask:0xf bank_mask:0xf bound_ctrl:1
	v_add_f32_dpp v46, v46, v46 quad_perm:[2,3,0,1] row_mask:0xf bank_mask:0xf bound_ctrl:1
	v_add_f32_dpp v248, v248, v248 quad_perm:[2,3,0,1] row_mask:0xf bank_mask:0xf bound_ctrl:1
	s_nop 0
	v_add_f32_dpp v232, v232, v232 row_half_mirror row_mask:0xf bank_mask:0xf bound_ctrl:1
	v_add_f32_dpp v240, v240, v240 row_half_mirror row_mask:0xf bank_mask:0xf bound_ctrl:1
	v_add_f32_dpp v46, v46, v46 row_half_mirror row_mask:0xf bank_mask:0xf bound_ctrl:1
	v_add_f32_dpp v248, v248, v248 row_half_mirror row_mask:0xf bank_mask:0xf bound_ctrl:1
	s_nop 0
	v_max3_f32 v4, v4, v232, v240
	v_max3_f32 v4, v4, v46, v248
	s_add_u32 s6, s6, 4
	s_addc_u32 s7, s7, 0
	s_cmp_eq_u32 s6, 16
	s_cbranch_scc1 .LBB0_377
	s_branch .LBB0_368
